# scan loop: global loads spread across the iteration (top/after-MFMA/after-barrier) instead of a burst at the top
# speedup vs baseline: 1.0200x; 1.0063x over previous
; #define LAS __attribute__((address_space(3)))
; DI void scan_load(ScanFrags& F, const unsigned char* ws, int c, int h, int dir, int sl, int w, int lane) {
;     const size_t blk = (size_t)((c * 4 + h) * 2 + dir);
;     const bf16_t* QT = (const bf16_t*)(ws + WS_U) + blk * 16384 + lane * 8;
;     const bf16_t* KH = (const bf16_t*)(ws + WS_KH) + blk * 16384 + lane * 8;
;     const bf16_t* AM = (const bf16_t*)(ws + WS_AM) + blk * 4096 + lane * 8;
; #pragma unroll
;     for (int mb = 0; mb < 2; ++mb)
; #pragma unroll
;         for (int s = 0; s < 2; ++s) F.qa[mb][s] = *(const bf16x8*)(QT + ((w * 2 + mb) * 2 + s) * 512);
; #pragma unroll
;     for (int s = 0; s < 4; ++s) F.ka[s] = *(const bf16x8*)(KH + (w * 4 + s) * 512);
; #pragma unroll
;     for (int mb = 0; mb < 2; ++mb) F.aa[mb] = w < 4 ? *(const bf16x8*)(AM + ((w * 2 + mb)) * 512) : (bf16x8){0, 0, 0, 0, 0, 0, 0, 0};
; DI void phase_scan(const Params& p, LAS unsigned char* lds, unsigned char* ldsg, int j, int conv_rows, int next_layer) {
;     ...
;         for (int n = 0; n < 260; ++n) {
;             const int c = scan_chunk(n, b, dir);
;             scan_load(nn, p.ws, scan_chunk(n < 258 ? n + 2 : 259, b, dir), h, dir, sl, w, lane);
;             const bf16x8 sb0 = pack8(S, 0), sb1 = pack8(S, 1);
;             bf16x8 vb[4]; f32x4 dd[4];
;             {
;                 unsigned vo = (unsigned)(SCAN_VB_OFF + (n & 1) * 4096 + lane * 16), dofs = (unsigned)(SCAN_DD_OFF + (n & 1) * 1024 + (32 * w + 4 * hh) * 4);
;                 asm volatile("" : "+v"(vo), "+v"(dofs));
; #pragma unroll
;                 for (int s = 0; s < 4; ++s) { vb[s] = *(const LAS bf16x8*)(lds + vo + s * 1024); dd[s] = *(const LAS f32x4*)(lds + dofs + s * 32); }
;             }
;             const bf16x8 vw = (w & 3) == 0 ? vb[0] : ((w & 3) == 1 ? vb[1] : ((w & 3) == 2 ? vb[2] : vb[3]));
.LBB0_536:
.Lscp0_top_a:
	s_add_i32 s58, s57, -1
	s_min_u32 s34, s58, 0x101
	s_add_i32 s36, s34, -2
	s_sub_i32 s37, 0x101, s34
	s_and_b64 s[34:35], s[30:31], exec
	s_cselect_b32 s34, s36, s37
	s_add_i32 s34, s34, s56
	s_lshl_b32 s34, s34, 2
	s_or_b32 s34, s34, s54
	s_mov_b32 s88, s34
	s_ashr_i32 s89, s34, 31
	s_lshl_b64 s[88:89], s[88:89], 15
	s_lshl_b32 s35, s34, 1
	s_or_b32 s36, s35, s55
	s_ashr_i32 s37, s36, 31
	s_lshl_b64 s[86:87], s[36:37], 10
	s_lshl_b64 s[38:39], s[36:37], 15
	v_lshl_add_u64 v[52:53], v[220:221], 0, s[38:39]
	v_lshl_add_u64 v[54:55], v[222:223], 0, s[38:39]
	s_lshl_b64 s[90:91], s[36:37], 13
	v_lshl_add_u64 v[216:217], v[226:227], 0, s[90:91]
	global_load_dwordx4 v[76:79], v[52:53], off
	global_load_dwordx4 v[84:87], v[52:53], off offset:1024
	v_mov_b32_e32 v164, v50
	v_mov_b32_e32 v165, v50
	v_mov_b32_e32 v166, v50
	v_mov_b32_e32 v167, v50
	v_mov_b32_e32 v172, v50
	v_mov_b32_e32 v173, v50
	v_mov_b32_e32 v174, v50
	v_mov_b32_e32 v175, v50
	s_and_b32 s38, s58, 1
	v_lshl_or_b32 v18, s38, 12, v238
	v_lshl_add_u32 v19, s38, 10, v239
	v_cmp_lt_i32_e32 vcc, 0, v240
	v_add_u32_e32 v19, 0, v19
	v_add_u32_e32 v18, 0, v18
	ds_read_b128 v[200:203], v19
	ds_read_b128 v[196:199], v19 offset:32
	ds_read_b128 v[192:195], v18
	ds_read_b128 v[188:191], v18 offset:1024
	ds_read_b128 v[184:187], v18 offset:2048
	ds_read_b128 v[180:183], v18 offset:3072
	ds_read_b128 v[204:207], v19 offset:64
	ds_read_b128 v[208:211], v19 offset:96
	s_waitcnt lgkmcnt(5)
	v_mov_b64_e32 v[214:215], v[194:195]
	v_mov_b64_e32 v[212:213], v[192:193]
	s_and_saveexec_b64 s[34:35], vcc
	s_cbranch_execz .Lscp0_a_550
	v_cmp_ne_u32_e32 vcc, 1, v240
	s_and_saveexec_b64 s[36:37], vcc
	s_xor_b64 s[36:37], exec, s[36:37]
	s_cbranch_execz .Lscp0_a_547
	s_waitcnt lgkmcnt(2)
	v_cndmask_b32_e64 v215, v183, v187, s[12:13]
	v_cndmask_b32_e64 v214, v182, v186, s[12:13]
	v_cndmask_b32_e64 v213, v181, v185, s[12:13]
	v_cndmask_b32_e64 v212, v180, v184, s[12:13]

; #define LAS __attribute__((address_space(3)))
; DI unsigned pk2(float lo, float hi) { f32x2 v = {lo, hi}; bfv2 b = __builtin_convertvector(v, bfv2); return __builtin_bit_cast(unsigned, b); }
; DI void scan_load(ScanFrags& F, const unsigned char* ws, int c, int h, int dir, int sl, int w, int lane) {
;     ...
;         for (int s = 0; s < 2; ++s) F.qa[mb][s] = *(const bf16x8*)(QT + ((w * 2 + mb) * 2 + s) * 512);
; #pragma unroll
;     for (int s = 0; s < 4; ++s) F.ka[s] = *(const bf16x8*)(KH + (w * 4 + s) * 512);
; #pragma unroll
;     for (int mb = 0; mb < 2; ++mb) F.aa[mb] = w < 4 ? *(const bf16x8*)(AM + ((w * 2 + mb)) * 512) : (bf16x8){0, 0, 0, 0, 0, 0, 0, 0};
; DI void phase_scan(const Params& p, LAS unsigned char* lds, unsigned char* ldsg, int j, int conv_rows, int next_layer) {
;     ...
;             bf16x8 aa0 = cur.aa[0], aa1 = cur.aa[1];
;             unsigned rbo = (unsigned)(((n & 1) * 8 + w) * 4608 + r * 72 + hh * 8);
;             asm volatile("" : "+v"(rbo));
;             LAS unsigned char* rb = lds + rbo;
; #pragma unroll
;             for (int mb = 0; mb < 2; ++mb) {
;                 f32x16 o;
; #pragma unroll
;                 for (int i = 0; i < 16; ++i) o[i] = 0.f;
;                 o = __builtin_amdgcn_mfma_f32_32x32x16_bf16(sb0, cur.qa[mb][0], o, 0, 0, 0);
;                 o = __builtin_amdgcn_mfma_f32_32x32x16_bf16(sb1, cur.qa[mb][1], o, 0, 0, 0);
;                 o = __builtin_amdgcn_mfma_f32_32x32x16_bf16(vw, mb ? aa1 : aa0, o, 0, 0, 0);
; #pragma unroll
;                 for (int g = 0; g < 4; ++g) { u32x2 pk; pk.x = pk2(o[4 * g], o[4 * g + 1]); pk.y = pk2(o[4 * g + 2], o[4 * g + 3]);
;                     *(LAS u32x2*)(rb + mb * 2304 + g * 16) = pk; }
;             }
;             scan_stage_store(nxt, lds, (n + 1) & 1, tid);
.Lscp0_a_550:
	s_or_b64 exec, exec, s[34:35]
	s_cmp_lg_u64 s[4:5], 0
	s_cbranch_scc1 .Lw1a_p0a
	s_waitcnt vmcnt(12)
	s_branch .Lw1b_p0a
.Lw1a_p0a:
	s_waitcnt vmcnt(15)
.Lw1b_p0a:
	v_cvt_pk_bf16_f32 v34, v2, v3
	v_cvt_pk_bf16_f32 v35, v4, v5
	v_cvt_pk_bf16_f32 v36, v6, v7
	v_cvt_pk_bf16_f32 v37, v8, v9
	v_cvt_pk_bf16_f32 v250, v10, v11
	v_cvt_pk_bf16_f32 v251, v12, v13
	v_mfma_f32_32x32x16_bf16 v[18:33], v[34:37], v[120:123], 0
	v_cvt_pk_bf16_f32 v252, v14, v15
	v_cvt_pk_bf16_f32 v253, v16, v17
	v_lshl_add_u32 v51, s38, 3, v1
	v_mad_u32_u24 v51, v51, s51, v241
	s_and_b32 s39, s57, 1
	v_add_u32_e32 v51, 0, v51
	v_mfma_f32_32x32x16_bf16 v[34:49], v[34:37], v[108:111], 0
	v_mfma_f32_32x32x16_bf16 v[18:33], v[250:253], v[116:119], v[18:33]
	v_mfma_f32_32x32x16_bf16 v[34:49], v[250:253], v[104:107], v[34:49]
	v_mfma_f32_32x32x16_bf16 v[18:33], v[212:215], v[124:127], v[18:33]
	v_mfma_f32_32x32x16_bf16 v[34:49], v[212:215], v[112:115], v[34:49]
	global_load_dwordx4 v[92:95], v[52:53], off offset:2048
	global_load_dwordx4 v[100:103], v[52:53], off offset:3072
	s_and_saveexec_b64 s[92:93], s[4:5]
	s_cbranch_execz .Laask_p0a
	global_load_dwordx4 v[164:167], v[216:217], off
	global_load_dwordx4 v[172:175], v[216:217], off offset:1024
.Laask_p0a:
	s_or_b64 exec, exec, s[92:93]
	s_nop 10
	v_cvt_pk_bf16_f32 v18, v18, v19
	v_cvt_pk_bf16_f32 v19, v20, v21
	v_cvt_pk_bf16_f32 v20, v22, v23
	v_cvt_pk_bf16_f32 v21, v24, v25
	ds_write2_b64 v51, v[18:19], v[20:21] offset1:2
	v_cvt_pk_bf16_f32 v18, v26, v27
	v_cvt_pk_bf16_f32 v19, v28, v29
	v_cvt_pk_bf16_f32 v20, v30, v31
	v_cvt_pk_bf16_f32 v21, v32, v33
	ds_write2_b64 v51, v[18:19], v[20:21] offset0:4 offset1:6
	v_cvt_pk_bf16_f32 v18, v34, v35
	v_cvt_pk_bf16_f32 v19, v36, v37
	v_cvt_pk_bf16_f32 v20, v38, v39
	v_cvt_pk_bf16_f32 v21, v40, v41
	v_add_u32_e32 v22, 0x800, v51
	ds_write2_b64 v22, v[18:19], v[20:21] offset0:32 offset1:34
	v_cvt_pk_bf16_f32 v18, v42, v43
	v_cvt_pk_bf16_f32 v19, v44, v45
	v_cvt_pk_bf16_f32 v20, v46, v47
	v_cvt_pk_bf16_f32 v21, v48, v49
	ds_write2_b64 v22, v[18:19], v[20:21] offset0:36 offset1:38
	s_and_saveexec_b64 s[34:35], s[6:7]
	s_xor_b64 s[34:35], exec, s[34:35]
	s_cbranch_execz .Lscp0_a_554
	s_and_saveexec_b64 s[36:37], s[10:11]
	s_cbranch_execz .Lscp0_a_553
	v_lshl_add_u32 v18, s39, 10, v219
	v_add_u32_e32 v18, 0xfffff000, v18
	s_waitcnt vmcnt(9)
	ds_write_b128 v18, v[72:75]
	v_lshl_add_u64 v[18:19], v[224:225], 0, s[86:87]
	v_add_co_u32_e32 v18, vcc, 0x36fff000, v18
	s_nop 1
	v_addc_co_u32_e32 v19, vcc, 0, v19, vcc
	global_load_dwordx4 v[72:75], v[18:19], off

; #define LAS __attribute__((address_space(3)))
; DI unsigned pk2(float lo, float hi) { f32x2 v = {lo, hi}; bfv2 b = __builtin_convertvector(v, bfv2); return __builtin_bit_cast(unsigned, b); }
; DI float lo_bf(unsigned u) { return __uint_as_float(u << 16); }
; DI float hi_bf(unsigned u) { return __uint_as_float(u & 0xffff0000u); }
; DI void phase_scan(const Params& p, LAS unsigned char* lds, unsigned char* ldsg, int j, int conv_rows, int next_layer) {
;     ...
;         for (int n = 0; n < 260; ++n) {
;             const int c = scan_chunk(n, b, dir);
;             scan_load(nn, p.ws, scan_chunk(n < 258 ? n + 2 : 259, b, dir), h, dir, sl, w, lane);
;             const bf16x8 sb0 = pack8(S, 0), sb1 = pack8(S, 1);
;             bf16x8 vb[4]; f32x4 dd[4];
;             {
;                 unsigned vo = (unsigned)(SCAN_VB_OFF + (n & 1) * 4096 + lane * 16), dofs = (unsigned)(SCAN_DD_OFF + (n & 1) * 1024 + (32 * w + 4 * hh) * 4);
;                 asm volatile("" : "+v"(vo), "+v"(dofs));
; #pragma unroll
;                 for (int s = 0; s < 4; ++s) { vb[s] = *(const LAS bf16x8*)(lds + vo + s * 1024); dd[s] = *(const LAS f32x4*)(lds + dofs + s * 32); }
;             }
;             const bf16x8 vw = (w & 3) == 0 ? vb[0] : ((w & 3) == 1 ? vb[1] : ((w & 3) == 2 ? vb[2] : vb[3]));
;     ...
; #pragma unroll
;             for (int i = 0; i < 16; ++i) S[i] *= dd[i >> 2][i & 3];
; #pragma unroll
;             for (int s = 0; s < 4; ++s) S = __builtin_amdgcn_mfma_f32_32x32x16_bf16(cur.ka[s], vb[s], S, 0, 0, 0);
;             __syncthreads();
;             {
;                 const int i = tid >> 3, vq = (tid & 7) * 4;
;                 unsigned rpo = (unsigned)((n & 1) * 8 * 4608 + i * 72 + vq * 2);
;                 asm volatile("" : "+v"(rpo));
;                 const LAS unsigned char* rp = lds + rpo;
;                 float a0 = 0.f, a1 = 0.f, a2 = 0.f, a3 = 0.f;
; #pragma unroll
;                 for (int ww = 0; ww < 8; ++ww) { const u32x2 q = *(const LAS u32x2*)(rp + ww * 4608); a0 += lo_bf(q.x); a1 += hi_bf(q.x); a2 += lo_bf(q.y); a3 += hi_bf(q.y); }
;                 u32x2 ov; ov.x = pk2(a0, a1); ov.y = pk2(a2, a3);
;                 *(u32x2*)(H + (size_t)(64 * c + i) * HE + (dir ? 2048 : 0) + h * 256 + 32 * sl + vq) = ov;
;             }
;             cur = nxt; nxt = nn;
.Lscp0_a_556:
	s_or_b64 exec, exec, s[34:35]
	s_waitcnt lgkmcnt(4)
	v_pk_mul_f32 v[16:17], v[16:17], v[210:211]
	v_pk_mul_f32 v[12:13], v[12:13], v[206:207]
	v_pk_mul_f32 v[8:9], v[8:9], v[198:199]
	v_pk_mul_f32 v[4:5], v[4:5], v[202:203]
	v_pk_mul_f32 v[2:3], v[2:3], v[200:201]
	v_pk_mul_f32 v[14:15], v[14:15], v[208:209]
	v_pk_mul_f32 v[10:11], v[10:11], v[204:205]
	v_pk_mul_f32 v[6:7], v[6:7], v[196:197]
	s_mul_i32 s38, s38, 0x9000
	v_add_u32_e32 v18, s38, v243
	v_mfma_f32_32x32x16_bf16 v[2:17], v[68:71], v[192:195], v[2:17]
	s_waitcnt lgkmcnt(0)
	s_barrier
	s_add_i32 s36, s57, -5
	v_add_u32_e32 v30, 0, v18
	ds_read2st64_b64 v[18:21], v30 offset1:9
	v_mfma_f32_32x32x16_bf16 v[2:17], v[64:67], v[188:191], v[2:17]
	ds_read2st64_b64 v[22:25], v30 offset0:18 offset1:27
	ds_read2st64_b64 v[26:29], v30 offset0:36 offset1:45
	ds_read2st64_b64 v[30:33], v30 offset0:54 offset1:63
	global_load_dwordx4 v[132:135], v[54:55], off
	global_load_dwordx4 v[144:147], v[54:55], off offset:1024
	global_load_dwordx4 v[148:151], v[54:55], off offset:2048
	global_load_dwordx4 v[156:159], v[54:55], off offset:3072
	s_and_b64 s[34:35], s[30:31], exec
	s_cselect_b32 s34, s36, s20
	s_waitcnt lgkmcnt(3)
	v_lshlrev_b32_e32 v34, 16, v18
	v_and_b32_e32 v35, 0xffff0000, v18
	v_lshlrev_b32_e32 v18, 16, v19
	v_and_b32_e32 v19, 0xffff0000, v19
	v_mfma_f32_32x32x16_bf16 v[2:17], v[60:63], v[184:187], v[2:17]
	v_lshlrev_b32_e32 v36, 16, v20
	v_and_b32_e32 v37, 0xffff0000, v20
	v_add_f32_e64 v18, v18, 0
	v_add_f32_e64 v19, v19, 0
	v_lshlrev_b32_e32 v20, 16, v21
	v_and_b32_e32 v21, 0xffff0000, v21
	v_pk_add_f32 v[34:35], v[34:35], 0 op_sel_hi:[1,0]
	v_pk_add_f32 v[18:19], v[18:19], v[20:21]
	s_waitcnt lgkmcnt(2)
	v_lshlrev_b32_e32 v20, 16, v23
	v_and_b32_e32 v21, 0xffff0000, v23
	v_pk_add_f32 v[34:35], v[34:35], v[36:37]
	v_lshlrev_b32_e32 v36, 16, v22
	v_and_b32_e32 v37, 0xffff0000, v22
	v_pk_add_f32 v[18:19], v[18:19], v[20:21]
	v_lshlrev_b32_e32 v20, 16, v25
	v_and_b32_e32 v21, 0xffff0000, v25
	v_mfma_f32_32x32x16_bf16 v[2:17], v[56:59], v[180:183], v[2:17]
	v_add_f32_e64 v34, v34, v36
	v_add_f32_e64 v35, v35, v37
	v_lshlrev_b32_e32 v36, 16, v24
	v_and_b32_e32 v37, 0xffff0000, v24
	v_add_f32_e64 v18, v18, v20
	v_add_f32_e64 v19, v19, v21
	s_waitcnt lgkmcnt(1)
	v_lshlrev_b32_e32 v20, 16, v27
	v_and_b32_e32 v21, 0xffff0000, v27
	v_pk_add_f32 v[34:35], v[34:35], v[36:37]
	v_lshlrev_b32_e32 v36, 16, v26
	v_and_b32_e32 v37, 0xffff0000, v26
	v_pk_add_f32 v[18:19], v[18:19], v[20:21]
	v_lshlrev_b32_e32 v20, 16, v29
	v_and_b32_e32 v21, 0xffff0000, v29
	v_pk_add_f32 v[34:35], v[34:35], v[36:37]
	v_lshlrev_b32_e32 v36, 16, v28
	v_and_b32_e32 v37, 0xffff0000, v28
	v_pk_add_f32 v[18:19], v[18:19], v[20:21]
	s_waitcnt lgkmcnt(0)
	v_lshlrev_b32_e32 v20, 16, v31
	v_and_b32_e32 v21, 0xffff0000, v31
	v_pk_add_f32 v[34:35], v[34:35], v[36:37]
	v_lshlrev_b32_e32 v36, 16, v30
	v_and_b32_e32 v37, 0xffff0000, v30
	v_pk_add_f32 v[18:19], v[18:19], v[20:21]
	v_lshlrev_b32_e32 v20, 16, v33
	v_and_b32_e32 v21, 0xffff0000, v33
	s_add_i32 s34, s34, s56
	v_pk_add_f32 v[34:35], v[34:35], v[36:37]
	v_lshlrev_b32_e32 v36, 16, v32
	v_and_b32_e32 v37, 0xffff0000, v32
	v_pk_add_f32 v[18:19], v[18:19], v[20:21]
	v_pk_add_f32 v[34:35], v[34:35], v[36:37]
	v_cvt_pk_bf16_f32 v21, v18, v19
	v_lshl_add_u32 v18, s34, 6, v242
	s_add_i32 s20, s20, -1
	s_add_i32 s57, s57, 1
	v_cvt_pk_bf16_f32 v20, v34, v35
	v_mad_i64_i32 v[18:19], s[34:35], v18, s52, v[232:233]
	s_cmp_eq_u32 s20, -1
	global_store_dwordx2 v[18:19], v[20:21], off
	s_cbranch_scc1 .LBB0_432
.Lscp0_top_b:
	s_add_i32 s58, s57, -1
	s_min_u32 s34, s58, 0x101
	s_add_i32 s36, s34, -2
	s_sub_i32 s37, 0x101, s34
	s_and_b64 s[34:35], s[30:31], exec
	s_cselect_b32 s34, s36, s37
	s_add_i32 s34, s34, s56
	s_lshl_b32 s34, s34, 2
	s_or_b32 s34, s34, s54
	s_mov_b32 s88, s34
	s_ashr_i32 s89, s34, 31
	s_lshl_b64 s[88:89], s[88:89], 15
	s_lshl_b32 s35, s34, 1
	s_or_b32 s36, s35, s55
	s_ashr_i32 s37, s36, 31
	s_lshl_b64 s[86:87], s[36:37], 10
	s_lshl_b64 s[38:39], s[36:37], 15
	v_lshl_add_u64 v[52:53], v[220:221], 0, s[38:39]
	v_lshl_add_u64 v[54:55], v[222:223], 0, s[38:39]
	s_lshl_b64 s[90:91], s[36:37], 13
	v_lshl_add_u64 v[216:217], v[226:227], 0, s[90:91]
	global_load_dwordx4 v[120:123], v[52:53], off
	global_load_dwordx4 v[116:119], v[52:53], off offset:1024
	v_mov_b32_e32 v124, v50
	v_mov_b32_e32 v125, v50
	v_mov_b32_e32 v126, v50
	v_mov_b32_e32 v127, v50
	v_mov_b32_e32 v112, v50
	v_mov_b32_e32 v113, v50
	v_mov_b32_e32 v114, v50
	v_mov_b32_e32 v115, v50
	s_and_b32 s38, s58, 1
	v_lshl_or_b32 v18, s38, 12, v238
	v_lshl_add_u32 v19, s38, 10, v239
	v_cmp_lt_i32_e32 vcc, 0, v240
	v_add_u32_e32 v19, 0, v19
	v_add_u32_e32 v18, 0, v18
	ds_read_b128 v[200:203], v19
	ds_read_b128 v[196:199], v19 offset:32
	ds_read_b128 v[192:195], v18
	ds_read_b128 v[188:191], v18 offset:1024
	ds_read_b128 v[184:187], v18 offset:2048
	ds_read_b128 v[180:183], v18 offset:3072
	ds_read_b128 v[204:207], v19 offset:64
	ds_read_b128 v[208:211], v19 offset:96
	s_waitcnt lgkmcnt(5)
	v_mov_b64_e32 v[214:215], v[194:195]
	v_mov_b64_e32 v[212:213], v[192:193]
	s_and_saveexec_b64 s[34:35], vcc
	s_cbranch_execz .Lscp0_b_550
	v_cmp_ne_u32_e32 vcc, 1, v240
	s_and_saveexec_b64 s[36:37], vcc
	s_xor_b64 s[36:37], exec, s[36:37]
	s_cbranch_execz .Lscp0_b_547
	s_waitcnt lgkmcnt(2)
	v_cndmask_b32_e64 v215, v183, v187, s[12:13]
	v_cndmask_b32_e64 v214, v182, v186, s[12:13]
	v_cndmask_b32_e64 v213, v181, v185, s[12:13]
	v_cndmask_b32_e64 v212, v180, v184, s[12:13]

; DI void scan_load(ScanFrags& F, const unsigned char* ws, int c, int h, int dir, int sl, int w, int lane) {
;     ...
;         for (int s = 0; s < 2; ++s) F.qa[mb][s] = *(const bf16x8*)(QT + ((w * 2 + mb) * 2 + s) * 512);
; #pragma unroll
;     for (int s = 0; s < 4; ++s) F.ka[s] = *(const bf16x8*)(KH + (w * 4 + s) * 512);
; #pragma unroll
;     for (int mb = 0; mb < 2; ++mb) F.aa[mb] = w < 4 ? *(const bf16x8*)(AM + ((w * 2 + mb)) * 512) : (bf16x8){0, 0, 0, 0, 0, 0, 0, 0};
; DI void phase_scan(const Params& p, LAS unsigned char* lds, unsigned char* ldsg, int j, int conv_rows, int next_layer) {
;     ...
;             for (int mb = 0; mb < 2; ++mb) {
;                 f32x16 o;
; #pragma unroll
;                 for (int i = 0; i < 16; ++i) o[i] = 0.f;
;                 o = __builtin_amdgcn_mfma_f32_32x32x16_bf16(sb0, cur.qa[mb][0], o, 0, 0, 0);
;                 o = __builtin_amdgcn_mfma_f32_32x32x16_bf16(sb1, cur.qa[mb][1], o, 0, 0, 0);
;                 o = __builtin_amdgcn_mfma_f32_32x32x16_bf16(vw, mb ? aa1 : aa0, o, 0, 0, 0);
.Lw1b_p0b:
	v_cvt_pk_bf16_f32 v34, v2, v3
	v_cvt_pk_bf16_f32 v35, v4, v5
	v_cvt_pk_bf16_f32 v36, v6, v7
	v_cvt_pk_bf16_f32 v37, v8, v9
	v_cvt_pk_bf16_f32 v250, v10, v11
	v_cvt_pk_bf16_f32 v251, v12, v13
	v_mfma_f32_32x32x16_bf16 v[18:33], v[34:37], v[80:83], 0
	v_cvt_pk_bf16_f32 v252, v14, v15
	v_cvt_pk_bf16_f32 v253, v16, v17
	v_lshl_add_u32 v51, s38, 3, v1
	v_mad_u32_u24 v51, v51, s51, v241
	s_and_b32 s39, s57, 1
	v_add_u32_e32 v51, 0, v51
	v_mfma_f32_32x32x16_bf16 v[34:49], v[34:37], v[128:131], 0
	v_mfma_f32_32x32x16_bf16 v[18:33], v[250:253], v[88:91], v[18:33]
	v_mfma_f32_32x32x16_bf16 v[34:49], v[250:253], v[96:99], v[34:49]
	v_mfma_f32_32x32x16_bf16 v[18:33], v[212:215], v[176:179], v[18:33]
	v_mfma_f32_32x32x16_bf16 v[34:49], v[212:215], v[168:171], v[34:49]
	global_load_dwordx4 v[108:111], v[52:53], off offset:2048
	global_load_dwordx4 v[104:107], v[52:53], off offset:3072
	s_and_saveexec_b64 s[92:93], s[4:5]
	s_cbranch_execz .Laask_p0b
	global_load_dwordx4 v[124:127], v[216:217], off
	global_load_dwordx4 v[112:115], v[216:217], off offset:1024

; #define LAS __attribute__((address_space(3)))
; DI unsigned pk2(float lo, float hi) { f32x2 v = {lo, hi}; bfv2 b = __builtin_convertvector(v, bfv2); return __builtin_bit_cast(unsigned, b); }
; DI float lo_bf(unsigned u) { return __uint_as_float(u << 16); }
; DI float hi_bf(unsigned u) { return __uint_as_float(u & 0xffff0000u); }
; DI void phase_scan(const Params& p, LAS unsigned char* lds, unsigned char* ldsg, int j, int conv_rows, int next_layer) {
;     ...
;         for (int n = 0; n < 260; ++n) {
;             const int c = scan_chunk(n, b, dir);
;             scan_load(nn, p.ws, scan_chunk(n < 258 ? n + 2 : 259, b, dir), h, dir, sl, w, lane);
;             const bf16x8 sb0 = pack8(S, 0), sb1 = pack8(S, 1);
;             bf16x8 vb[4]; f32x4 dd[4];
;             {
;                 unsigned vo = (unsigned)(SCAN_VB_OFF + (n & 1) * 4096 + lane * 16), dofs = (unsigned)(SCAN_DD_OFF + (n & 1) * 1024 + (32 * w + 4 * hh) * 4);
;                 asm volatile("" : "+v"(vo), "+v"(dofs));
; #pragma unroll
;                 for (int s = 0; s < 4; ++s) { vb[s] = *(const LAS bf16x8*)(lds + vo + s * 1024); dd[s] = *(const LAS f32x4*)(lds + dofs + s * 32); }
;             }
;             const bf16x8 vw = (w & 3) == 0 ? vb[0] : ((w & 3) == 1 ? vb[1] : ((w & 3) == 2 ? vb[2] : vb[3]));
;     ...
; #pragma unroll
;             for (int i = 0; i < 16; ++i) S[i] *= dd[i >> 2][i & 3];
; #pragma unroll
;             for (int s = 0; s < 4; ++s) S = __builtin_amdgcn_mfma_f32_32x32x16_bf16(cur.ka[s], vb[s], S, 0, 0, 0);
;             __syncthreads();
;             {
;                 const int i = tid >> 3, vq = (tid & 7) * 4;
;                 unsigned rpo = (unsigned)((n & 1) * 8 * 4608 + i * 72 + vq * 2);
;                 asm volatile("" : "+v"(rpo));
;                 const LAS unsigned char* rp = lds + rpo;
;                 float a0 = 0.f, a1 = 0.f, a2 = 0.f, a3 = 0.f;
; #pragma unroll
;                 for (int ww = 0; ww < 8; ++ww) { const u32x2 q = *(const LAS u32x2*)(rp + ww * 4608); a0 += lo_bf(q.x); a1 += hi_bf(q.x); a2 += lo_bf(q.y); a3 += hi_bf(q.y); }
;                 u32x2 ov; ov.x = pk2(a0, a1); ov.y = pk2(a2, a3);
;                 *(u32x2*)(H + (size_t)(64 * c + i) * HE + (dir ? 2048 : 0) + h * 256 + 32 * sl + vq) = ov;
;             }
;             cur = nxt; nxt = nn;
.Lscp0_b_556:
	s_or_b64 exec, exec, s[34:35]
	s_waitcnt lgkmcnt(4)
	v_pk_mul_f32 v[16:17], v[16:17], v[210:211]
	v_pk_mul_f32 v[12:13], v[12:13], v[206:207]
	v_pk_mul_f32 v[8:9], v[8:9], v[198:199]
	v_pk_mul_f32 v[4:5], v[4:5], v[202:203]
	v_pk_mul_f32 v[2:3], v[2:3], v[200:201]
	v_pk_mul_f32 v[14:15], v[14:15], v[208:209]
	v_pk_mul_f32 v[10:11], v[10:11], v[204:205]
	v_pk_mul_f32 v[6:7], v[6:7], v[196:197]
	s_mul_i32 s38, s38, 0x9000
	v_add_u32_e32 v18, s38, v243
	v_mfma_f32_32x32x16_bf16 v[2:17], v[136:139], v[192:195], v[2:17]
	s_waitcnt lgkmcnt(0)
	s_barrier
	s_add_i32 s36, s57, -5
	v_add_u32_e32 v30, 0, v18
	ds_read2st64_b64 v[18:21], v30 offset1:9
	v_mfma_f32_32x32x16_bf16 v[2:17], v[140:143], v[188:191], v[2:17]
	ds_read2st64_b64 v[22:25], v30 offset0:18 offset1:27
	ds_read2st64_b64 v[26:29], v30 offset0:36 offset1:45
	ds_read2st64_b64 v[30:33], v30 offset0:54 offset1:63
	global_load_dwordx4 v[68:71], v[54:55], off
	global_load_dwordx4 v[64:67], v[54:55], off offset:1024
	global_load_dwordx4 v[60:63], v[54:55], off offset:2048
	global_load_dwordx4 v[56:59], v[54:55], off offset:3072
	s_and_b64 s[34:35], s[30:31], exec
	s_cselect_b32 s34, s36, s20
	s_waitcnt lgkmcnt(3)
	v_lshlrev_b32_e32 v34, 16, v18
	v_and_b32_e32 v35, 0xffff0000, v18
	v_lshlrev_b32_e32 v18, 16, v19
	v_and_b32_e32 v19, 0xffff0000, v19
	v_mfma_f32_32x32x16_bf16 v[2:17], v[152:155], v[184:187], v[2:17]
	v_lshlrev_b32_e32 v36, 16, v20
	v_and_b32_e32 v37, 0xffff0000, v20
	v_add_f32_e64 v18, v18, 0
	v_add_f32_e64 v19, v19, 0
	v_lshlrev_b32_e32 v20, 16, v21
	v_and_b32_e32 v21, 0xffff0000, v21
	v_pk_add_f32 v[34:35], v[34:35], 0 op_sel_hi:[1,0]
	v_pk_add_f32 v[18:19], v[18:19], v[20:21]
	s_waitcnt lgkmcnt(2)
	v_lshlrev_b32_e32 v20, 16, v23
	v_and_b32_e32 v21, 0xffff0000, v23
	v_pk_add_f32 v[34:35], v[34:35], v[36:37]
	v_lshlrev_b32_e32 v36, 16, v22
	v_and_b32_e32 v37, 0xffff0000, v22
	v_pk_add_f32 v[18:19], v[18:19], v[20:21]
	v_lshlrev_b32_e32 v20, 16, v25
	v_and_b32_e32 v21, 0xffff0000, v25
	v_mfma_f32_32x32x16_bf16 v[2:17], v[160:163], v[180:183], v[2:17]
	v_add_f32_e64 v34, v34, v36
	v_add_f32_e64 v35, v35, v37
	v_lshlrev_b32_e32 v36, 16, v24
	v_and_b32_e32 v37, 0xffff0000, v24
	v_add_f32_e64 v18, v18, v20
	v_add_f32_e64 v19, v19, v21
	s_waitcnt lgkmcnt(1)
	v_lshlrev_b32_e32 v20, 16, v27
	v_and_b32_e32 v21, 0xffff0000, v27
	v_pk_add_f32 v[34:35], v[34:35], v[36:37]
	v_lshlrev_b32_e32 v36, 16, v26
	v_and_b32_e32 v37, 0xffff0000, v26
	v_pk_add_f32 v[18:19], v[18:19], v[20:21]
	v_lshlrev_b32_e32 v20, 16, v29
	v_and_b32_e32 v21, 0xffff0000, v29
	v_pk_add_f32 v[34:35], v[34:35], v[36:37]
	v_lshlrev_b32_e32 v36, 16, v28
	v_and_b32_e32 v37, 0xffff0000, v28
	v_pk_add_f32 v[18:19], v[18:19], v[20:21]
	s_waitcnt lgkmcnt(0)
	v_lshlrev_b32_e32 v20, 16, v31
	v_and_b32_e32 v21, 0xffff0000, v31
	v_pk_add_f32 v[34:35], v[34:35], v[36:37]
	v_lshlrev_b32_e32 v36, 16, v30
	v_and_b32_e32 v37, 0xffff0000, v30
	v_pk_add_f32 v[18:19], v[18:19], v[20:21]
	v_lshlrev_b32_e32 v20, 16, v33
	v_and_b32_e32 v21, 0xffff0000, v33
	s_add_i32 s34, s34, s56
	v_pk_add_f32 v[34:35], v[34:35], v[36:37]
	v_lshlrev_b32_e32 v36, 16, v32
	v_and_b32_e32 v37, 0xffff0000, v32
	v_pk_add_f32 v[18:19], v[18:19], v[20:21]
	v_pk_add_f32 v[34:35], v[34:35], v[36:37]
	v_cvt_pk_bf16_f32 v21, v18, v19
	v_lshl_add_u32 v18, s34, 6, v242
	s_add_i32 s20, s20, -1
	s_add_i32 s57, s57, 1
	v_cvt_pk_bf16_f32 v20, v34, v35
	v_mad_i64_i32 v[18:19], s[34:35], v18, s52, v[232:233]
	s_cmp_eq_u32 s20, -1
	global_store_dwordx2 v[18:19], v[20:21], off
	s_cbranch_scc1 .LBB0_432
.Lscp0_top_c:
	s_add_i32 s58, s57, -1
	s_min_u32 s34, s58, 0x101
	s_add_i32 s36, s34, -2
	s_sub_i32 s37, 0x101, s34
	s_and_b64 s[34:35], s[30:31], exec
	s_cselect_b32 s34, s36, s37
	s_add_i32 s34, s34, s56
	s_lshl_b32 s34, s34, 2
	s_or_b32 s34, s34, s54
	s_mov_b32 s88, s34
	s_ashr_i32 s89, s34, 31
	s_lshl_b64 s[88:89], s[88:89], 15
	s_lshl_b32 s35, s34, 1
	s_or_b32 s36, s35, s55
	s_ashr_i32 s37, s36, 31
	s_lshl_b64 s[86:87], s[36:37], 10
	s_lshl_b64 s[38:39], s[36:37], 15
	v_lshl_add_u64 v[52:53], v[220:221], 0, s[38:39]
	v_lshl_add_u64 v[54:55], v[222:223], 0, s[38:39]
	s_lshl_b64 s[90:91], s[36:37], 13
	v_lshl_add_u64 v[216:217], v[226:227], 0, s[90:91]
	global_load_dwordx4 v[80:83], v[52:53], off
	global_load_dwordx4 v[88:91], v[52:53], off offset:1024
	v_mov_b32_e32 v176, v50
	v_mov_b32_e32 v177, v50
	v_mov_b32_e32 v178, v50
	v_mov_b32_e32 v179, v50
	v_mov_b32_e32 v168, v50
	v_mov_b32_e32 v169, v50
	v_mov_b32_e32 v170, v50
	v_mov_b32_e32 v171, v50
	s_and_b32 s38, s58, 1
	v_lshl_or_b32 v18, s38, 12, v238
	v_lshl_add_u32 v19, s38, 10, v239
	v_cmp_lt_i32_e32 vcc, 0, v240
	v_add_u32_e32 v19, 0, v19
	v_add_u32_e32 v18, 0, v18
	ds_read_b128 v[200:203], v19
	ds_read_b128 v[196:199], v19 offset:32
	ds_read_b128 v[192:195], v18
	ds_read_b128 v[188:191], v18 offset:1024
	ds_read_b128 v[184:187], v18 offset:2048
	ds_read_b128 v[180:183], v18 offset:3072
	ds_read_b128 v[204:207], v19 offset:64
	ds_read_b128 v[208:211], v19 offset:96
	s_waitcnt lgkmcnt(5)
	v_mov_b64_e32 v[214:215], v[194:195]
	v_mov_b64_e32 v[212:213], v[192:193]
	s_and_saveexec_b64 s[34:35], vcc
	s_cbranch_execz .Lscp0_c_550
	v_cmp_ne_u32_e32 vcc, 1, v240
	s_and_saveexec_b64 s[36:37], vcc
	s_xor_b64 s[36:37], exec, s[36:37]
	s_cbranch_execz .Lscp0_c_547
	s_waitcnt lgkmcnt(2)
	v_cndmask_b32_e64 v215, v183, v187, s[12:13]
	v_cndmask_b32_e64 v214, v182, v186, s[12:13]
	v_cndmask_b32_e64 v213, v181, v185, s[12:13]
	v_cndmask_b32_e64 v212, v180, v184, s[12:13]

; DI void scan_load(ScanFrags& F, const unsigned char* ws, int c, int h, int dir, int sl, int w, int lane) {
;     ...
;         for (int s = 0; s < 2; ++s) F.qa[mb][s] = *(const bf16x8*)(QT + ((w * 2 + mb) * 2 + s) * 512);
; #pragma unroll
;     for (int s = 0; s < 4; ++s) F.ka[s] = *(const bf16x8*)(KH + (w * 4 + s) * 512);
; #pragma unroll
;     for (int mb = 0; mb < 2; ++mb) F.aa[mb] = w < 4 ? *(const bf16x8*)(AM + ((w * 2 + mb)) * 512) : (bf16x8){0, 0, 0, 0, 0, 0, 0, 0};
; DI void phase_scan(const Params& p, LAS unsigned char* lds, unsigned char* ldsg, int j, int conv_rows, int next_layer) {
;     ...
;             for (int mb = 0; mb < 2; ++mb) {
;                 f32x16 o;
; #pragma unroll
;                 for (int i = 0; i < 16; ++i) o[i] = 0.f;
;                 o = __builtin_amdgcn_mfma_f32_32x32x16_bf16(sb0, cur.qa[mb][0], o, 0, 0, 0);
;                 o = __builtin_amdgcn_mfma_f32_32x32x16_bf16(sb1, cur.qa[mb][1], o, 0, 0, 0);
;                 o = __builtin_amdgcn_mfma_f32_32x32x16_bf16(vw, mb ? aa1 : aa0, o, 0, 0, 0);
.Lw1b_p0c:
	v_cvt_pk_bf16_f32 v34, v2, v3
	v_cvt_pk_bf16_f32 v35, v4, v5
	v_cvt_pk_bf16_f32 v36, v6, v7
	v_cvt_pk_bf16_f32 v37, v8, v9
	v_cvt_pk_bf16_f32 v250, v10, v11
	v_cvt_pk_bf16_f32 v251, v12, v13
	v_mfma_f32_32x32x16_bf16 v[18:33], v[34:37], v[76:79], 0
	v_cvt_pk_bf16_f32 v252, v14, v15
	v_cvt_pk_bf16_f32 v253, v16, v17
	v_lshl_add_u32 v51, s38, 3, v1
	v_mad_u32_u24 v51, v51, s51, v241
	s_and_b32 s39, s57, 1
	v_add_u32_e32 v51, 0, v51
	v_mfma_f32_32x32x16_bf16 v[34:49], v[34:37], v[92:95], 0
	v_mfma_f32_32x32x16_bf16 v[18:33], v[250:253], v[84:87], v[18:33]
	v_mfma_f32_32x32x16_bf16 v[34:49], v[250:253], v[100:103], v[34:49]
	v_mfma_f32_32x32x16_bf16 v[18:33], v[212:215], v[164:167], v[18:33]
	v_mfma_f32_32x32x16_bf16 v[34:49], v[212:215], v[172:175], v[34:49]
	global_load_dwordx4 v[128:131], v[52:53], off offset:2048
	global_load_dwordx4 v[96:99], v[52:53], off offset:3072
	s_and_saveexec_b64 s[92:93], s[4:5]
	s_cbranch_execz .Laask_p0c
	global_load_dwordx4 v[176:179], v[216:217], off
	global_load_dwordx4 v[168:171], v[216:217], off offset:1024

; #define LAS __attribute__((address_space(3)))
; DI unsigned pk2(float lo, float hi) { f32x2 v = {lo, hi}; bfv2 b = __builtin_convertvector(v, bfv2); return __builtin_bit_cast(unsigned, b); }
; DI float lo_bf(unsigned u) { return __uint_as_float(u << 16); }
; DI float hi_bf(unsigned u) { return __uint_as_float(u & 0xffff0000u); }
; DI void phase_scan(const Params& p, LAS unsigned char* lds, unsigned char* ldsg, int j, int conv_rows, int next_layer) {
;     ...
; #pragma unroll
;             for (int i = 0; i < 16; ++i) S[i] *= dd[i >> 2][i & 3];
; #pragma unroll
;             for (int s = 0; s < 4; ++s) S = __builtin_amdgcn_mfma_f32_32x32x16_bf16(cur.ka[s], vb[s], S, 0, 0, 0);
;             __syncthreads();
;             {
;                 const int i = tid >> 3, vq = (tid & 7) * 4;
;                 unsigned rpo = (unsigned)((n & 1) * 8 * 4608 + i * 72 + vq * 2);
;                 asm volatile("" : "+v"(rpo));
;                 const LAS unsigned char* rp = lds + rpo;
;                 float a0 = 0.f, a1 = 0.f, a2 = 0.f, a3 = 0.f;
; #pragma unroll
;                 for (int ww = 0; ww < 8; ++ww) { const u32x2 q = *(const LAS u32x2*)(rp + ww * 4608); a0 += lo_bf(q.x); a1 += hi_bf(q.x); a2 += lo_bf(q.y); a3 += hi_bf(q.y); }
;                 u32x2 ov; ov.x = pk2(a0, a1); ov.y = pk2(a2, a3);
;                 *(u32x2*)(H + (size_t)(64 * c + i) * HE + (dir ? 2048 : 0) + h * 256 + 32 * sl + vq) = ov;
;             }
;             cur = nxt; nxt = nn;
.Lscp0_c_556:
	s_or_b64 exec, exec, s[34:35]
	s_waitcnt lgkmcnt(4)
	v_pk_mul_f32 v[16:17], v[16:17], v[210:211]
	v_pk_mul_f32 v[12:13], v[12:13], v[206:207]
	v_pk_mul_f32 v[8:9], v[8:9], v[198:199]
	v_pk_mul_f32 v[4:5], v[4:5], v[202:203]
	v_pk_mul_f32 v[2:3], v[2:3], v[200:201]
	v_pk_mul_f32 v[14:15], v[14:15], v[208:209]
	v_pk_mul_f32 v[10:11], v[10:11], v[204:205]
	v_pk_mul_f32 v[6:7], v[6:7], v[196:197]
	s_mul_i32 s38, s38, 0x9000
	v_add_u32_e32 v18, s38, v243
	v_mfma_f32_32x32x16_bf16 v[2:17], v[132:135], v[192:195], v[2:17]
	s_waitcnt lgkmcnt(0)
	s_barrier
	s_add_i32 s36, s57, -5
	v_add_u32_e32 v30, 0, v18
	ds_read2st64_b64 v[18:21], v30 offset1:9
	v_mfma_f32_32x32x16_bf16 v[2:17], v[144:147], v[188:191], v[2:17]
	ds_read2st64_b64 v[22:25], v30 offset0:18 offset1:27
	ds_read2st64_b64 v[26:29], v30 offset0:36 offset1:45
	ds_read2st64_b64 v[30:33], v30 offset0:54 offset1:63
	global_load_dwordx4 v[136:139], v[54:55], off
	global_load_dwordx4 v[140:143], v[54:55], off offset:1024
	global_load_dwordx4 v[152:155], v[54:55], off offset:2048
	global_load_dwordx4 v[160:163], v[54:55], off offset:3072
	s_and_b64 s[34:35], s[30:31], exec
	s_cselect_b32 s34, s36, s20
	s_waitcnt lgkmcnt(3)
	v_lshlrev_b32_e32 v34, 16, v18
	v_and_b32_e32 v35, 0xffff0000, v18
	v_lshlrev_b32_e32 v18, 16, v19
	v_and_b32_e32 v19, 0xffff0000, v19
	v_mfma_f32_32x32x16_bf16 v[2:17], v[148:151], v[184:187], v[2:17]
	v_lshlrev_b32_e32 v36, 16, v20
	v_and_b32_e32 v37, 0xffff0000, v20
	v_add_f32_e64 v18, v18, 0
	v_add_f32_e64 v19, v19, 0
	v_lshlrev_b32_e32 v20, 16, v21
	v_and_b32_e32 v21, 0xffff0000, v21
	v_pk_add_f32 v[34:35], v[34:35], 0 op_sel_hi:[1,0]
	v_pk_add_f32 v[18:19], v[18:19], v[20:21]
	s_waitcnt lgkmcnt(2)
	v_lshlrev_b32_e32 v20, 16, v23
	v_and_b32_e32 v21, 0xffff0000, v23
	v_pk_add_f32 v[34:35], v[34:35], v[36:37]
	v_lshlrev_b32_e32 v36, 16, v22
	v_and_b32_e32 v37, 0xffff0000, v22
	v_pk_add_f32 v[18:19], v[18:19], v[20:21]
	v_lshlrev_b32_e32 v20, 16, v25
	v_and_b32_e32 v21, 0xffff0000, v25
	v_mfma_f32_32x32x16_bf16 v[2:17], v[156:159], v[180:183], v[2:17]
	v_add_f32_e64 v34, v34, v36
	v_add_f32_e64 v35, v35, v37
	v_lshlrev_b32_e32 v36, 16, v24
	v_and_b32_e32 v37, 0xffff0000, v24
	v_add_f32_e64 v18, v18, v20
	v_add_f32_e64 v19, v19, v21
	s_waitcnt lgkmcnt(1)
	v_lshlrev_b32_e32 v20, 16, v27
	v_and_b32_e32 v21, 0xffff0000, v27
	v_pk_add_f32 v[34:35], v[34:35], v[36:37]
	v_lshlrev_b32_e32 v36, 16, v26
	v_and_b32_e32 v37, 0xffff0000, v26
	v_pk_add_f32 v[18:19], v[18:19], v[20:21]
	v_lshlrev_b32_e32 v20, 16, v29
	v_and_b32_e32 v21, 0xffff0000, v29
	v_pk_add_f32 v[34:35], v[34:35], v[36:37]
	v_lshlrev_b32_e32 v36, 16, v28
	v_and_b32_e32 v37, 0xffff0000, v28
	v_pk_add_f32 v[18:19], v[18:19], v[20:21]
	s_waitcnt lgkmcnt(0)
	v_lshlrev_b32_e32 v20, 16, v31
	v_and_b32_e32 v21, 0xffff0000, v31
	v_pk_add_f32 v[34:35], v[34:35], v[36:37]
	v_lshlrev_b32_e32 v36, 16, v30
	v_and_b32_e32 v37, 0xffff0000, v30
	v_pk_add_f32 v[18:19], v[18:19], v[20:21]
	v_lshlrev_b32_e32 v20, 16, v33
	v_and_b32_e32 v21, 0xffff0000, v33
	s_add_i32 s34, s34, s56
	v_pk_add_f32 v[34:35], v[34:35], v[36:37]
	v_lshlrev_b32_e32 v36, 16, v32
	v_and_b32_e32 v37, 0xffff0000, v32
	v_pk_add_f32 v[18:19], v[18:19], v[20:21]
	v_pk_add_f32 v[34:35], v[34:35], v[36:37]
	v_cvt_pk_bf16_f32 v21, v18, v19
	v_lshl_add_u32 v18, s34, 6, v242
	s_add_i32 s20, s20, -1
	s_add_i32 s57, s57, 1
	v_cvt_pk_bf16_f32 v20, v34, v35
	v_mad_i64_i32 v[18:19], s[34:35], v18, s52, v[232:233]
	s_cmp_eq_u32 s20, -1
	global_store_dwordx2 v[18:19], v[20:21], off
	s_cbranch_scc1 .LBB0_432
	s_branch .Lscp0_top_a

; #define LAS __attribute__((address_space(3)))
; DI unsigned pk2(float lo, float hi) { f32x2 v = {lo, hi}; bfv2 b = __builtin_convertvector(v, bfv2); return __builtin_bit_cast(unsigned, b); }
; DI float lo_bf(unsigned u) { return __uint_as_float(u << 16); }
; DI float hi_bf(unsigned u) { return __uint_as_float(u & 0xffff0000u); }
; DI void phase_scan(const Params& p, LAS unsigned char* lds, unsigned char* ldsg, int j, int conv_rows, int next_layer) {
;     ...
; #pragma unroll
;             for (int i = 0; i < 16; ++i) S[i] *= dd[i >> 2][i & 3];
; #pragma unroll
;             for (int s = 0; s < 4; ++s) S = __builtin_amdgcn_mfma_f32_32x32x16_bf16(cur.ka[s], vb[s], S, 0, 0, 0);
;             __syncthreads();
;             {
;                 const int i = tid >> 3, vq = (tid & 7) * 4;
;                 unsigned rpo = (unsigned)((n & 1) * 8 * 4608 + i * 72 + vq * 2);
;                 asm volatile("" : "+v"(rpo));
;                 const LAS unsigned char* rp = lds + rpo;
;                 float a0 = 0.f, a1 = 0.f, a2 = 0.f, a3 = 0.f;
; #pragma unroll
;                 for (int ww = 0; ww < 8; ++ww) { const u32x2 q = *(const LAS u32x2*)(rp + ww * 4608); a0 += lo_bf(q.x); a1 += hi_bf(q.x); a2 += lo_bf(q.y); a3 += hi_bf(q.y); }
;                 u32x2 ov; ov.x = pk2(a0, a1); ov.y = pk2(a2, a3);
;                 *(u32x2*)(H + (size_t)(64 * c + i) * HE + (dir ? 2048 : 0) + h * 256 + 32 * sl + vq) = ov;
;             }
;             cur = nxt; nxt = nn;
.Lscp1_a_1735:
	s_or_b64 exec, exec, s[34:35]
	s_waitcnt lgkmcnt(4)
	v_pk_mul_f32 v[16:17], v[16:17], v[210:211]
	v_pk_mul_f32 v[12:13], v[12:13], v[206:207]
	v_pk_mul_f32 v[8:9], v[8:9], v[198:199]
	v_pk_mul_f32 v[4:5], v[4:5], v[202:203]
	v_pk_mul_f32 v[2:3], v[2:3], v[200:201]
	v_pk_mul_f32 v[14:15], v[14:15], v[208:209]
	v_pk_mul_f32 v[10:11], v[10:11], v[204:205]
	v_pk_mul_f32 v[6:7], v[6:7], v[196:197]
	s_mul_i32 s38, s38, 0x9000
	v_add_u32_e32 v18, s38, v243
	v_mfma_f32_32x32x16_bf16 v[2:17], v[68:71], v[192:195], v[2:17]
	s_waitcnt lgkmcnt(0)
	s_barrier
	s_add_i32 s36, s57, -5
	v_add_u32_e32 v30, 0, v18
	ds_read2st64_b64 v[18:21], v30 offset1:9
	v_mfma_f32_32x32x16_bf16 v[2:17], v[64:67], v[188:191], v[2:17]
	ds_read2st64_b64 v[22:25], v30 offset0:18 offset1:27
	ds_read2st64_b64 v[26:29], v30 offset0:36 offset1:45
	ds_read2st64_b64 v[30:33], v30 offset0:54 offset1:63
	global_load_dwordx4 v[132:135], v[54:55], off
	global_load_dwordx4 v[144:147], v[54:55], off offset:1024
	global_load_dwordx4 v[148:151], v[54:55], off offset:2048
	global_load_dwordx4 v[156:159], v[54:55], off offset:3072
	s_and_b64 s[34:35], s[30:31], exec
	s_cselect_b32 s34, s36, s24
	s_waitcnt lgkmcnt(3)
	v_lshlrev_b32_e32 v34, 16, v18
	v_and_b32_e32 v35, 0xffff0000, v18
	v_lshlrev_b32_e32 v18, 16, v19
	v_and_b32_e32 v19, 0xffff0000, v19
	v_mfma_f32_32x32x16_bf16 v[2:17], v[60:63], v[184:187], v[2:17]
	v_lshlrev_b32_e32 v36, 16, v20
	v_and_b32_e32 v37, 0xffff0000, v20
	v_add_f32_e64 v18, v18, 0
	v_add_f32_e64 v19, v19, 0
	v_lshlrev_b32_e32 v20, 16, v21
	v_and_b32_e32 v21, 0xffff0000, v21
	v_pk_add_f32 v[34:35], v[34:35], 0 op_sel_hi:[1,0]
	v_pk_add_f32 v[18:19], v[18:19], v[20:21]
	s_waitcnt lgkmcnt(2)
	v_lshlrev_b32_e32 v20, 16, v23
	v_and_b32_e32 v21, 0xffff0000, v23
	v_pk_add_f32 v[34:35], v[34:35], v[36:37]
	v_lshlrev_b32_e32 v36, 16, v22
	v_and_b32_e32 v37, 0xffff0000, v22
	v_pk_add_f32 v[18:19], v[18:19], v[20:21]
	v_lshlrev_b32_e32 v20, 16, v25
	v_and_b32_e32 v21, 0xffff0000, v25
	v_mfma_f32_32x32x16_bf16 v[2:17], v[56:59], v[180:183], v[2:17]
	v_add_f32_e64 v34, v34, v36
	v_add_f32_e64 v35, v35, v37
	v_lshlrev_b32_e32 v36, 16, v24
	v_and_b32_e32 v37, 0xffff0000, v24
	v_add_f32_e64 v18, v18, v20
	v_add_f32_e64 v19, v19, v21
	s_waitcnt lgkmcnt(1)
	v_lshlrev_b32_e32 v20, 16, v27
	v_and_b32_e32 v21, 0xffff0000, v27
	v_pk_add_f32 v[34:35], v[34:35], v[36:37]
	v_lshlrev_b32_e32 v36, 16, v26
	v_and_b32_e32 v37, 0xffff0000, v26
	v_pk_add_f32 v[18:19], v[18:19], v[20:21]
	v_lshlrev_b32_e32 v20, 16, v29
	v_and_b32_e32 v21, 0xffff0000, v29
	v_pk_add_f32 v[34:35], v[34:35], v[36:37]
	v_lshlrev_b32_e32 v36, 16, v28
	v_and_b32_e32 v37, 0xffff0000, v28
	v_pk_add_f32 v[18:19], v[18:19], v[20:21]
	s_waitcnt lgkmcnt(0)
	v_lshlrev_b32_e32 v20, 16, v31
	v_and_b32_e32 v21, 0xffff0000, v31
	v_pk_add_f32 v[34:35], v[34:35], v[36:37]
	v_lshlrev_b32_e32 v36, 16, v30
	v_and_b32_e32 v37, 0xffff0000, v30
	v_pk_add_f32 v[18:19], v[18:19], v[20:21]
	v_lshlrev_b32_e32 v20, 16, v33
	v_and_b32_e32 v21, 0xffff0000, v33
	s_add_i32 s34, s34, s56
	v_pk_add_f32 v[34:35], v[34:35], v[36:37]
	v_lshlrev_b32_e32 v36, 16, v32
	v_and_b32_e32 v37, 0xffff0000, v32
	v_pk_add_f32 v[18:19], v[18:19], v[20:21]
	v_pk_add_f32 v[34:35], v[34:35], v[36:37]
	v_cvt_pk_bf16_f32 v21, v18, v19
	v_lshl_add_u32 v18, s34, 6, v242
	s_add_i32 s24, s24, -1
	s_add_i32 s57, s57, 1
	v_cvt_pk_bf16_f32 v20, v34, v35
	v_mad_i64_i32 v[18:19], s[34:35], v18, s52, v[232:233]
	s_cmp_eq_u32 s24, -1
	global_store_dwordx2 v[18:19], v[20:21], off
	s_cbranch_scc1 .LBB0_1611

; #define LAS __attribute__((address_space(3)))
; DI unsigned pk2(float lo, float hi) { f32x2 v = {lo, hi}; bfv2 b = __builtin_convertvector(v, bfv2); return __builtin_bit_cast(unsigned, b); }
; DI float lo_bf(unsigned u) { return __uint_as_float(u << 16); }
; DI float hi_bf(unsigned u) { return __uint_as_float(u & 0xffff0000u); }
; DI void phase_scan(const Params& p, LAS unsigned char* lds, unsigned char* ldsg, int j, int conv_rows, int next_layer) {
;     ...
; #pragma unroll
;             for (int i = 0; i < 16; ++i) S[i] *= dd[i >> 2][i & 3];
; #pragma unroll
;             for (int s = 0; s < 4; ++s) S = __builtin_amdgcn_mfma_f32_32x32x16_bf16(cur.ka[s], vb[s], S, 0, 0, 0);
;             __syncthreads();
;             {
;                 const int i = tid >> 3, vq = (tid & 7) * 4;
;                 unsigned rpo = (unsigned)((n & 1) * 8 * 4608 + i * 72 + vq * 2);
;                 asm volatile("" : "+v"(rpo));
;                 const LAS unsigned char* rp = lds + rpo;
;                 float a0 = 0.f, a1 = 0.f, a2 = 0.f, a3 = 0.f;
; #pragma unroll
;                 for (int ww = 0; ww < 8; ++ww) { const u32x2 q = *(const LAS u32x2*)(rp + ww * 4608); a0 += lo_bf(q.x); a1 += hi_bf(q.x); a2 += lo_bf(q.y); a3 += hi_bf(q.y); }
;                 u32x2 ov; ov.x = pk2(a0, a1); ov.y = pk2(a2, a3);
;                 *(u32x2*)(H + (size_t)(64 * c + i) * HE + (dir ? 2048 : 0) + h * 256 + 32 * sl + vq) = ov;
;             }
;             cur = nxt; nxt = nn;
.Lscp1_b_1735:
	s_or_b64 exec, exec, s[34:35]
	s_waitcnt lgkmcnt(4)
	v_pk_mul_f32 v[16:17], v[16:17], v[210:211]
	v_pk_mul_f32 v[12:13], v[12:13], v[206:207]
	v_pk_mul_f32 v[8:9], v[8:9], v[198:199]
	v_pk_mul_f32 v[4:5], v[4:5], v[202:203]
	v_pk_mul_f32 v[2:3], v[2:3], v[200:201]
	v_pk_mul_f32 v[14:15], v[14:15], v[208:209]
	v_pk_mul_f32 v[10:11], v[10:11], v[204:205]
	v_pk_mul_f32 v[6:7], v[6:7], v[196:197]
	s_mul_i32 s38, s38, 0x9000
	v_add_u32_e32 v18, s38, v243
	v_mfma_f32_32x32x16_bf16 v[2:17], v[136:139], v[192:195], v[2:17]
	s_waitcnt lgkmcnt(0)
	s_barrier
	s_add_i32 s36, s57, -5
	v_add_u32_e32 v30, 0, v18
	ds_read2st64_b64 v[18:21], v30 offset1:9
	v_mfma_f32_32x32x16_bf16 v[2:17], v[140:143], v[188:191], v[2:17]
	ds_read2st64_b64 v[22:25], v30 offset0:18 offset1:27
	ds_read2st64_b64 v[26:29], v30 offset0:36 offset1:45
	ds_read2st64_b64 v[30:33], v30 offset0:54 offset1:63
	global_load_dwordx4 v[68:71], v[54:55], off
	global_load_dwordx4 v[64:67], v[54:55], off offset:1024
	global_load_dwordx4 v[60:63], v[54:55], off offset:2048
	global_load_dwordx4 v[56:59], v[54:55], off offset:3072
	s_and_b64 s[34:35], s[30:31], exec
	s_cselect_b32 s34, s36, s24
	s_waitcnt lgkmcnt(3)
	v_lshlrev_b32_e32 v34, 16, v18
	v_and_b32_e32 v35, 0xffff0000, v18
	v_lshlrev_b32_e32 v18, 16, v19
	v_and_b32_e32 v19, 0xffff0000, v19
	v_mfma_f32_32x32x16_bf16 v[2:17], v[152:155], v[184:187], v[2:17]
	v_lshlrev_b32_e32 v36, 16, v20
	v_and_b32_e32 v37, 0xffff0000, v20
	v_add_f32_e64 v18, v18, 0
	v_add_f32_e64 v19, v19, 0
	v_lshlrev_b32_e32 v20, 16, v21
	v_and_b32_e32 v21, 0xffff0000, v21
	v_pk_add_f32 v[34:35], v[34:35], 0 op_sel_hi:[1,0]
	v_pk_add_f32 v[18:19], v[18:19], v[20:21]
	s_waitcnt lgkmcnt(2)
	v_lshlrev_b32_e32 v20, 16, v23
	v_and_b32_e32 v21, 0xffff0000, v23
	v_pk_add_f32 v[34:35], v[34:35], v[36:37]
	v_lshlrev_b32_e32 v36, 16, v22
	v_and_b32_e32 v37, 0xffff0000, v22
	v_pk_add_f32 v[18:19], v[18:19], v[20:21]
	v_lshlrev_b32_e32 v20, 16, v25
	v_and_b32_e32 v21, 0xffff0000, v25
	v_mfma_f32_32x32x16_bf16 v[2:17], v[160:163], v[180:183], v[2:17]
	v_add_f32_e64 v34, v34, v36
	v_add_f32_e64 v35, v35, v37
	v_lshlrev_b32_e32 v36, 16, v24
	v_and_b32_e32 v37, 0xffff0000, v24
	v_add_f32_e64 v18, v18, v20
	v_add_f32_e64 v19, v19, v21
	s_waitcnt lgkmcnt(1)
	v_lshlrev_b32_e32 v20, 16, v27
	v_and_b32_e32 v21, 0xffff0000, v27
	v_pk_add_f32 v[34:35], v[34:35], v[36:37]
	v_lshlrev_b32_e32 v36, 16, v26
	v_and_b32_e32 v37, 0xffff0000, v26
	v_pk_add_f32 v[18:19], v[18:19], v[20:21]
	v_lshlrev_b32_e32 v20, 16, v29
	v_and_b32_e32 v21, 0xffff0000, v29
	v_pk_add_f32 v[34:35], v[34:35], v[36:37]
	v_lshlrev_b32_e32 v36, 16, v28
	v_and_b32_e32 v37, 0xffff0000, v28
	v_pk_add_f32 v[18:19], v[18:19], v[20:21]
	s_waitcnt lgkmcnt(0)
	v_lshlrev_b32_e32 v20, 16, v31
	v_and_b32_e32 v21, 0xffff0000, v31
	v_pk_add_f32 v[34:35], v[34:35], v[36:37]
	v_lshlrev_b32_e32 v36, 16, v30
	v_and_b32_e32 v37, 0xffff0000, v30
	v_pk_add_f32 v[18:19], v[18:19], v[20:21]
	v_lshlrev_b32_e32 v20, 16, v33
	v_and_b32_e32 v21, 0xffff0000, v33
	s_add_i32 s34, s34, s56
	v_pk_add_f32 v[34:35], v[34:35], v[36:37]
	v_lshlrev_b32_e32 v36, 16, v32
	v_and_b32_e32 v37, 0xffff0000, v32
	v_pk_add_f32 v[18:19], v[18:19], v[20:21]
	v_pk_add_f32 v[34:35], v[34:35], v[36:37]
	v_cvt_pk_bf16_f32 v21, v18, v19
	v_lshl_add_u32 v18, s34, 6, v242
	s_add_i32 s24, s24, -1
	s_add_i32 s57, s57, 1
	v_cvt_pk_bf16_f32 v20, v34, v35
	v_mad_i64_i32 v[18:19], s[34:35], v18, s52, v[232:233]
	s_cmp_eq_u32 s24, -1
	global_store_dwordx2 v[18:19], v[20:21], off
	s_cbranch_scc1 .LBB0_1611

; #define LAS __attribute__((address_space(3)))
; DI unsigned pk2(float lo, float hi) { f32x2 v = {lo, hi}; bfv2 b = __builtin_convertvector(v, bfv2); return __builtin_bit_cast(unsigned, b); }
; DI float lo_bf(unsigned u) { return __uint_as_float(u << 16); }
; DI float hi_bf(unsigned u) { return __uint_as_float(u & 0xffff0000u); }
; DI void phase_scan(const Params& p, LAS unsigned char* lds, unsigned char* ldsg, int j, int conv_rows, int next_layer) {
;     ...
; #pragma unroll
;             for (int i = 0; i < 16; ++i) S[i] *= dd[i >> 2][i & 3];
; #pragma unroll
;             for (int s = 0; s < 4; ++s) S = __builtin_amdgcn_mfma_f32_32x32x16_bf16(cur.ka[s], vb[s], S, 0, 0, 0);
;             __syncthreads();
;             {
;                 const int i = tid >> 3, vq = (tid & 7) * 4;
;                 unsigned rpo = (unsigned)((n & 1) * 8 * 4608 + i * 72 + vq * 2);
;                 asm volatile("" : "+v"(rpo));
;                 const LAS unsigned char* rp = lds + rpo;
;                 float a0 = 0.f, a1 = 0.f, a2 = 0.f, a3 = 0.f;
; #pragma unroll
;                 for (int ww = 0; ww < 8; ++ww) { const u32x2 q = *(const LAS u32x2*)(rp + ww * 4608); a0 += lo_bf(q.x); a1 += hi_bf(q.x); a2 += lo_bf(q.y); a3 += hi_bf(q.y); }
;                 u32x2 ov; ov.x = pk2(a0, a1); ov.y = pk2(a2, a3);
;                 *(u32x2*)(H + (size_t)(64 * c + i) * HE + (dir ? 2048 : 0) + h * 256 + 32 * sl + vq) = ov;
;             }
;             cur = nxt; nxt = nn;
.Lscp1_c_1735:
	s_or_b64 exec, exec, s[34:35]
	s_waitcnt lgkmcnt(4)
	v_pk_mul_f32 v[16:17], v[16:17], v[210:211]
	v_pk_mul_f32 v[12:13], v[12:13], v[206:207]
	v_pk_mul_f32 v[8:9], v[8:9], v[198:199]
	v_pk_mul_f32 v[4:5], v[4:5], v[202:203]
	v_pk_mul_f32 v[2:3], v[2:3], v[200:201]
	v_pk_mul_f32 v[14:15], v[14:15], v[208:209]
	v_pk_mul_f32 v[10:11], v[10:11], v[204:205]
	v_pk_mul_f32 v[6:7], v[6:7], v[196:197]
	s_mul_i32 s38, s38, 0x9000
	v_add_u32_e32 v18, s38, v243
	v_mfma_f32_32x32x16_bf16 v[2:17], v[132:135], v[192:195], v[2:17]
	s_waitcnt lgkmcnt(0)
	s_barrier
	s_add_i32 s36, s57, -5
	v_add_u32_e32 v30, 0, v18
	ds_read2st64_b64 v[18:21], v30 offset1:9
	v_mfma_f32_32x32x16_bf16 v[2:17], v[144:147], v[188:191], v[2:17]
	ds_read2st64_b64 v[22:25], v30 offset0:18 offset1:27
	ds_read2st64_b64 v[26:29], v30 offset0:36 offset1:45
	ds_read2st64_b64 v[30:33], v30 offset0:54 offset1:63
	global_load_dwordx4 v[136:139], v[54:55], off
	global_load_dwordx4 v[140:143], v[54:55], off offset:1024
	global_load_dwordx4 v[152:155], v[54:55], off offset:2048
	global_load_dwordx4 v[160:163], v[54:55], off offset:3072
	s_and_b64 s[34:35], s[30:31], exec
	s_cselect_b32 s34, s36, s24
	s_waitcnt lgkmcnt(3)
	v_lshlrev_b32_e32 v34, 16, v18
	v_and_b32_e32 v35, 0xffff0000, v18
	v_lshlrev_b32_e32 v18, 16, v19
	v_and_b32_e32 v19, 0xffff0000, v19
	v_mfma_f32_32x32x16_bf16 v[2:17], v[148:151], v[184:187], v[2:17]
	v_lshlrev_b32_e32 v36, 16, v20
	v_and_b32_e32 v37, 0xffff0000, v20
	v_add_f32_e64 v18, v18, 0
	v_add_f32_e64 v19, v19, 0
	v_lshlrev_b32_e32 v20, 16, v21
	v_and_b32_e32 v21, 0xffff0000, v21
	v_pk_add_f32 v[34:35], v[34:35], 0 op_sel_hi:[1,0]
	v_pk_add_f32 v[18:19], v[18:19], v[20:21]
	s_waitcnt lgkmcnt(2)
	v_lshlrev_b32_e32 v20, 16, v23
	v_and_b32_e32 v21, 0xffff0000, v23
	v_pk_add_f32 v[34:35], v[34:35], v[36:37]
	v_lshlrev_b32_e32 v36, 16, v22
	v_and_b32_e32 v37, 0xffff0000, v22
	v_pk_add_f32 v[18:19], v[18:19], v[20:21]
	v_lshlrev_b32_e32 v20, 16, v25
	v_and_b32_e32 v21, 0xffff0000, v25
	v_mfma_f32_32x32x16_bf16 v[2:17], v[156:159], v[180:183], v[2:17]
	v_add_f32_e64 v34, v34, v36
	v_add_f32_e64 v35, v35, v37
	v_lshlrev_b32_e32 v36, 16, v24
	v_and_b32_e32 v37, 0xffff0000, v24
	v_add_f32_e64 v18, v18, v20
	v_add_f32_e64 v19, v19, v21
	s_waitcnt lgkmcnt(1)
	v_lshlrev_b32_e32 v20, 16, v27
	v_and_b32_e32 v21, 0xffff0000, v27
	v_pk_add_f32 v[34:35], v[34:35], v[36:37]
	v_lshlrev_b32_e32 v36, 16, v26
	v_and_b32_e32 v37, 0xffff0000, v26
	v_pk_add_f32 v[18:19], v[18:19], v[20:21]
	v_lshlrev_b32_e32 v20, 16, v29
	v_and_b32_e32 v21, 0xffff0000, v29
	v_pk_add_f32 v[34:35], v[34:35], v[36:37]
	v_lshlrev_b32_e32 v36, 16, v28
	v_and_b32_e32 v37, 0xffff0000, v28
	v_pk_add_f32 v[18:19], v[18:19], v[20:21]
	s_waitcnt lgkmcnt(0)
	v_lshlrev_b32_e32 v20, 16, v31
	v_and_b32_e32 v21, 0xffff0000, v31
	v_pk_add_f32 v[34:35], v[34:35], v[36:37]
	v_lshlrev_b32_e32 v36, 16, v30
	v_and_b32_e32 v37, 0xffff0000, v30
	v_pk_add_f32 v[18:19], v[18:19], v[20:21]
	v_lshlrev_b32_e32 v20, 16, v33
	v_and_b32_e32 v21, 0xffff0000, v33
	s_add_i32 s34, s34, s56
	v_pk_add_f32 v[34:35], v[34:35], v[36:37]
	v_lshlrev_b32_e32 v36, 16, v32
	v_and_b32_e32 v37, 0xffff0000, v32
	v_pk_add_f32 v[18:19], v[18:19], v[20:21]
	v_pk_add_f32 v[34:35], v[34:35], v[36:37]
	v_cvt_pk_bf16_f32 v21, v18, v19
	v_lshl_add_u32 v18, s34, 6, v242
	s_add_i32 s24, s24, -1
	s_add_i32 s57, s57, 1
	v_cvt_pk_bf16_f32 v20, v34, v35
	v_mad_i64_i32 v[18:19], s[34:35], v18, s52, v[232:233]
	s_cmp_eq_u32 s24, -1
	global_store_dwordx2 v[18:19], v[20:21], off
	s_cbranch_scc1 .LBB0_1611
	s_branch .Lscp1_top_a
